# v110 + scan step: next-step prefetch issue block moved from the step head into the MFMA section (under LDS/MFMA latency)
# speedup vs baseline: 1.0039x; 1.0012x over previous
.LBB0_447:
	ds_read_b128 v[110:113], v164 offset:17408
	ds_read_b128 v[114:117], v164 offset:17472
	ds_read_b128 v[144:147], v164 offset:17536
	ds_read_b128 v[148:151], v164 offset:17600
	ds_read_b128 v[152:155], v164 offset:21760
	ds_read_b128 v[170:173], v164 offset:21824
	ds_read_b128 v[174:177], v164 offset:21888
	ds_read_b128 v[178:181], v164 offset:21952
	s_waitcnt lgkmcnt(7)
	v_mfma_f32_16x16x32_bf16 v[110:113], v[110:113], v[94:97], 0
	s_waitcnt lgkmcnt(6)
	v_mfma_f32_16x16x32_bf16 v[110:113], v[114:117], v[98:101], v[110:113]
	s_waitcnt lgkmcnt(5)
	v_mfma_f32_16x16x32_bf16 v[110:113], v[144:147], v[102:105], v[110:113]
	s_waitcnt lgkmcnt(4)
	v_mfma_f32_16x16x32_bf16 v[110:113], v[148:151], v[106:109], v[110:113]
	ds_read_b128 v[114:117], v164 offset:26112
	ds_read_b128 v[144:147], v164 offset:26176
	ds_read_b128 v[148:151], v164 offset:26240
	ds_read_b128 v[182:185], v164 offset:26304
	s_cmp_eq_u32 s16, 63
	s_cbranch_scc1 .Lscan_noload
	s_add_i32 s30, s17, s16
	s_lshl_b64 s[34:35], s[30:31], 13
	s_lshl_b64 s[36:37], s[30:31], 14
	s_add_u32 s40, s22, s36
	s_addc_u32 s41, s23, s37
	v_lshl_add_u64 v[2:3], s[40:41], 0, v[138:139]
	v_lshl_add_u64 v[6:7], s[40:41], 0, v[140:141]
	s_add_u32 s40, s28, s36
	s_addc_u32 s41, s29, s37
	v_lshl_add_u64 v[18:19], v[128:129], 0, s[34:35]
	s_add_u32 s34, s24, s36
	s_addc_u32 s35, s25, s37
	v_lshl_add_u64 v[22:23], s[34:35], 0, v[138:139]
	v_lshl_add_u64 v[26:27], s[34:35], 0, v[140:141]
	s_lshl_b64 s[34:35], s[30:31], 15
	s_add_u32 s34, s26, s34
	s_addc_u32 s35, s27, s35
	v_lshl_add_u64 v[30:31], s[34:35], 0, v[120:121]
	v_lshl_add_u64 v[34:35], s[34:35], 0, v[122:123]
	v_lshl_add_u64 v[38:39], s[34:35], 0, v[124:125]
	v_lshl_add_u64 v[42:43], s[34:35], 0, v[126:127]
	s_add_u32 s34, s12, s6
	v_lshl_add_u64 v[10:11], s[40:41], 0, v[138:139]
	v_lshl_add_u64 v[14:15], s[40:41], 0, v[140:141]
	s_addc_u32 s35, s13, 0
	global_load_dwordx4 v[2:5], v[2:3], off
	s_nop 0
	global_load_dwordx4 v[6:9], v[6:7], off
	s_nop 0
	global_load_dwordx4 v[10:13], v[10:11], off
	s_nop 0
	global_load_dwordx4 v[14:17], v[14:15], off
	s_nop 0
	global_load_dwordx4 v[18:21], v[18:19], off
	s_nop 0
	global_load_dwordx4 v[22:25], v[22:23], off
	s_nop 0
	global_load_dwordx4 v[26:29], v[26:27], off
	s_nop 0
	global_load_dwordx4 v[30:33], v[30:31], off
	s_nop 0
	global_load_dwordx4 v[34:37], v[34:35], off
	s_nop 0
	global_load_dwordx4 v[38:41], v[38:39], off
	v_lshl_add_u64 v[54:55], v[136:137], 0, s[6:7]
	global_load_dword v162, v131, s[34:35]
	s_mov_b64 s[34:35], 0x48675000
	v_lshl_add_u64 v[56:57], v[54:55], 0, s[34:35]
	v_add_co_u32_e32 v54, vcc, 0x48675000, v54
	global_load_dwordx4 v[42:45], v[42:43], off
	s_nop 0
	v_addc_co_u32_e32 v55, vcc, 0, v55, vcc
	global_load_dwordx4 v[58:61], v[54:55], off
	s_nop 0
	global_load_dwordx4 v[54:57], v[56:57], off offset:16
.Lscan_noload:
	s_waitcnt lgkmcnt(7)
	v_mfma_f32_16x16x32_bf16 v[152:155], v[152:155], v[94:97], 0
	s_waitcnt lgkmcnt(6)
	v_mfma_f32_16x16x32_bf16 v[152:155], v[170:173], v[98:101], v[152:155]
	s_waitcnt lgkmcnt(5)
	v_mfma_f32_16x16x32_bf16 v[152:155], v[174:177], v[102:105], v[152:155]
	s_waitcnt lgkmcnt(4)
	v_mfma_f32_16x16x32_bf16 v[152:155], v[178:181], v[106:109], v[152:155]
	ds_read_b128 v[170:173], v164 offset:30464
	ds_read_b128 v[174:177], v164 offset:30528
	ds_read_b128 v[178:181], v164 offset:30592
	ds_read_b128 v[186:189], v164 offset:30656
	s_waitcnt lgkmcnt(7)
	v_mfma_f32_16x16x32_bf16 v[114:117], v[114:117], v[94:97], 0
	s_waitcnt lgkmcnt(6)
	v_mfma_f32_16x16x32_bf16 v[114:117], v[144:147], v[98:101], v[114:117]
	s_waitcnt lgkmcnt(5)
	v_mfma_f32_16x16x32_bf16 v[114:117], v[148:151], v[102:105], v[114:117]
	s_waitcnt lgkmcnt(4)
	v_mfma_f32_16x16x32_bf16 v[114:117], v[182:185], v[106:109], v[114:117]
	ds_read_b128 v[144:147], v164
	ds_read_b128 v[148:151], v164 offset:64
	ds_read_b128 v[182:185], v164 offset:128
	ds_read_b128 v[190:193], v164 offset:192
	s_waitcnt lgkmcnt(7)
	v_mfma_f32_16x16x32_bf16 v[170:173], v[170:173], v[94:97], 0
	s_waitcnt lgkmcnt(6)
	v_mfma_f32_16x16x32_bf16 v[170:173], v[174:177], v[98:101], v[170:173]
	s_waitcnt lgkmcnt(5)
	v_mfma_f32_16x16x32_bf16 v[170:173], v[178:181], v[102:105], v[170:173]
	s_waitcnt lgkmcnt(4)
	v_mfma_f32_16x16x32_bf16 v[170:173], v[186:189], v[106:109], v[170:173]
	ds_read_b128 v[174:177], v164 offset:4352
	ds_read_b128 v[178:181], v164 offset:4416
	ds_read_b128 v[186:189], v164 offset:4480
	ds_read_b128 v[194:197], v164 offset:4544
	v_add_u32_e32 v142, 0x400, v163
	ds_read2_b32 v[198:199], v163 offset1:132
	ds_read2_b32 v[200:201], v142 offset0:8 offset1:140
	s_waitcnt lgkmcnt(0)
	v_mfma_f32_16x16x32_bf16 v[144:147], v[144:147], v[94:97], v[198:201]
	v_mfma_f32_16x16x32_bf16 v[144:147], v[148:151], v[98:101], v[144:147]
	v_mfma_f32_16x16x32_bf16 v[144:147], v[182:185], v[102:105], v[144:147]
	v_mfma_f32_16x16x32_bf16 v[144:147], v[190:193], v[106:109], v[144:147]
	ds_read_b128 v[148:151], v164 offset:8704
	ds_read_b128 v[182:185], v164 offset:8768
	ds_read_b128 v[190:193], v164 offset:8832
	ds_read_b128 v[198:201], v164 offset:8896
	v_add_u32_e32 v142, 0x2000, v163
	ds_read2_b32 v[202:203], v142 offset0:64 offset1:196
	v_add_u32_e32 v142, 0x2400, v163
	ds_read2_b32 v[204:205], v142 offset0:72 offset1:204
	s_waitcnt lgkmcnt(0)
	v_mfma_f32_16x16x32_bf16 v[174:177], v[174:177], v[94:97], v[202:205]
	v_mfma_f32_16x16x32_bf16 v[174:177], v[178:181], v[98:101], v[174:177]
	v_mfma_f32_16x16x32_bf16 v[174:177], v[186:189], v[102:105], v[174:177]
	v_mfma_f32_16x16x32_bf16 v[174:177], v[194:197], v[106:109], v[174:177]
	ds_read_b128 v[178:181], v164 offset:13056
	ds_read_b128 v[186:189], v164 offset:13120
	ds_read_b128 v[194:197], v164 offset:13184
	ds_read_b128 v[202:205], v164 offset:13248
	v_add_u32_e32 v142, 0x4200, v163
	ds_read2_b32 v[206:207], v142 offset1:132
	v_add_u32_e32 v142, 0x4600, v163
	ds_read2_b32 v[208:209], v142 offset0:8 offset1:140
	s_waitcnt lgkmcnt(0)
	v_mfma_f32_16x16x32_bf16 v[148:151], v[148:151], v[94:97], v[206:209]
	v_mfma_f32_16x16x32_bf16 v[148:151], v[182:185], v[98:101], v[148:151]
	v_mfma_f32_16x16x32_bf16 v[148:151], v[190:193], v[102:105], v[148:151]
	v_mfma_f32_16x16x32_bf16 v[148:151], v[198:201], v[106:109], v[148:151]
	ds_read_b128 v[182:185], v165 offset:34816
	ds_read_b128 v[190:193], v165 offset:34880
	ds_read_b128 v[198:201], v165 offset:37120
	ds_read_b128 v[206:209], v165 offset:37184
	v_add_u32_e32 v142, 0x6200, v163
	ds_read2_b32 v[210:211], v142 offset0:64 offset1:196
	v_add_u32_e32 v142, 0x6600, v163
	ds_read2_b32 v[212:213], v142 offset0:72 offset1:204
	s_waitcnt lgkmcnt(0)
	v_mfma_f32_16x16x32_bf16 v[94:97], v[178:181], v[94:97], v[210:213]
	v_mfma_f32_16x16x32_bf16 v[94:97], v[186:189], v[98:101], v[94:97]
	v_mfma_f32_16x16x32_bf16 v[94:97], v[194:197], v[102:105], v[94:97]
	ds_read_b128 v[98:101], v165 offset:39424
	ds_read_b128 v[102:105], v165 offset:39488
	ds_read_b128 v[178:181], v165 offset:41728
	ds_read_b128 v[186:189], v165 offset:41792
	v_mfma_f32_16x16x32_bf16 v[94:97], v[202:205], v[106:109], v[94:97]
	v_cvt_pk_bf16_f32 v106, v144, v145
	v_cvt_pk_bf16_f32 v107, v146, v147
	v_cvt_pk_bf16_f32 v108, v174, v175
	v_cvt_pk_bf16_f32 v109, v176, v177
	v_cvt_pk_bf16_f32 v144, v148, v149
	v_cvt_pk_bf16_f32 v145, v150, v151
	v_mfma_f32_16x16x32_bf16 v[110:113], v[182:185], v[106:109], v[110:113]
	s_nop 0
	v_cvt_pk_bf16_f32 v146, v94, v95
	v_cvt_pk_bf16_f32 v147, v96, v97
	s_nop 1
	v_mfma_f32_16x16x32_bf16 v[94:97], v[190:193], v[144:147], v[110:113]
	v_mfma_f32_16x16x32_bf16 v[110:113], v[198:201], v[106:109], v[152:155]
	ds_read_b128 v[148:151], v165 offset:44032
	s_nop 1
	ds_read_b128 v[152:155], v165 offset:44096
	ds_read_b128 v[174:177], v165 offset:46336
	ds_read_b128 v[182:185], v165 offset:46400
	v_mfma_f32_16x16x32_bf16 v[110:113], v[206:209], v[144:147], v[110:113]
	s_waitcnt lgkmcnt(7)
	v_mfma_f32_16x16x32_bf16 v[98:101], v[98:101], v[106:109], v[114:117]
	s_waitcnt lgkmcnt(6)
	v_mfma_f32_16x16x32_bf16 v[98:101], v[102:105], v[144:147], v[98:101]
	s_waitcnt lgkmcnt(5)
	v_mfma_f32_16x16x32_bf16 v[102:105], v[178:181], v[106:109], v[170:173]
	s_waitcnt lgkmcnt(4)
	v_mfma_f32_16x16x32_bf16 v[102:105], v[186:189], v[144:147], v[102:105]
	ds_read_b128 v[114:117], v165 offset:48640
	ds_read_b128 v[170:173], v165 offset:48704
	ds_read_b128 v[178:181], v165 offset:50944
	ds_read_b128 v[186:189], v165 offset:51008
	v_pk_mul_f32 v[64:65], v[64:65], v[130:131] op_sel_hi:[1,0]
	v_pk_mul_f32 v[62:63], v[62:63], v[130:131] op_sel_hi:[1,0]
	v_pk_mul_f32 v[68:69], v[68:69], v[130:131] op_sel_hi:[1,0]
	v_pk_mul_f32 v[66:67], v[66:67], v[130:131] op_sel_hi:[1,0]
	s_waitcnt lgkmcnt(7)
	v_mfma_f32_16x16x32_bf16 v[62:65], v[148:151], v[106:109], v[62:65]
	v_mul_f32_e64 v76, v76, v130
	v_mul_f32_e64 v77, v77, v130
	v_pk_mul_f32 v[74:75], v[74:75], v[130:131] op_sel_hi:[1,0]
	v_pk_mul_f32 v[72:73], v[72:73], v[130:131] op_sel_hi:[1,0]
	s_waitcnt lgkmcnt(5)
	v_mfma_f32_16x16x32_bf16 v[66:69], v[174:177], v[106:109], v[66:69]
	v_mul_f32_e64 v70, v70, v130
	v_mul_f32_e64 v71, v71, v130
	v_pk_mul_f32 v[80:81], v[80:81], v[130:131] op_sel_hi:[1,0]
	v_pk_mul_f32 v[78:79], v[78:79], v[130:131] op_sel_hi:[1,0]
	v_mfma_f32_16x16x32_bf16 v[62:65], v[152:155], v[144:147], v[62:65]
	v_mul_f32_e64 v84, v84, v130
	v_mul_f32_e64 v85, v85, v130
	v_pk_mul_f32 v[82:83], v[82:83], v[130:131] op_sel_hi:[1,0]
	v_pk_mul_f32 v[88:89], v[88:89], v[130:131] op_sel_hi:[1,0]
	s_waitcnt lgkmcnt(4)
	v_mfma_f32_16x16x32_bf16 v[66:69], v[182:185], v[144:147], v[66:69]
	ds_read_b128 v[148:151], v165 offset:53248
	ds_read_b128 v[152:155], v165 offset:53312
	ds_read_b128 v[174:177], v165 offset:55552
	ds_read_b128 v[182:185], v165 offset:55616
	v_pk_mul_f32 v[86:87], v[86:87], v[130:131] op_sel_hi:[1,0]
	v_pk_mul_f32 v[92:93], v[92:93], v[130:131] op_sel_hi:[1,0]
	v_pk_mul_f32 v[90:91], v[90:91], v[130:131] op_sel_hi:[1,0]
	s_waitcnt lgkmcnt(7)
	v_mfma_f32_16x16x32_bf16 v[74:77], v[114:117], v[106:109], v[74:77]
	s_waitcnt lgkmcnt(5)
	v_mfma_f32_16x16x32_bf16 v[70:73], v[178:181], v[106:109], v[70:73]
	v_mfma_f32_16x16x32_bf16 v[74:77], v[170:173], v[144:147], v[74:77]
	s_waitcnt lgkmcnt(4)
	v_mfma_f32_16x16x32_bf16 v[70:73], v[186:189], v[144:147], v[70:73]
	ds_read_b128 v[114:117], v165 offset:57856
	ds_read_b128 v[170:173], v165 offset:57920
	ds_read_b128 v[178:181], v165 offset:60160
	ds_read_b128 v[186:189], v165 offset:60224
	s_waitcnt lgkmcnt(7)
	v_mfma_f32_16x16x32_bf16 v[78:81], v[148:151], v[106:109], v[78:81]
	s_waitcnt lgkmcnt(5)
	v_mfma_f32_16x16x32_bf16 v[82:85], v[174:177], v[106:109], v[82:85]
	v_mfma_f32_16x16x32_bf16 v[78:81], v[152:155], v[144:147], v[78:81]
	s_waitcnt lgkmcnt(4)
	v_mfma_f32_16x16x32_bf16 v[82:85], v[182:185], v[144:147], v[82:85]
	ds_write2_b32 v167, v94, v95 offset1:132
	v_add_u32_e32 v94, 0xf800, v166
	ds_write2_b32 v94, v96, v97 offset0:8 offset1:140
	v_add_u32_e32 v94, 0x2000, v167
	ds_write2_b32 v94, v110, v111 offset0:64 offset1:196
	v_add_u32_e32 v94, 0x2400, v167
	ds_write2_b32 v94, v112, v113 offset0:72 offset1:204
	v_add_u32_e32 v94, 0x4200, v167
	ds_write2_b32 v94, v98, v99 offset1:132
	v_add_u32_e32 v94, 0x4600, v167
	ds_write2_b32 v94, v100, v101 offset0:8 offset1:140
	v_add_u32_e32 v94, 0x6200, v167
	ds_write2_b32 v94, v102, v103 offset0:64 offset1:196
	v_add_u32_e32 v94, 0x6600, v167
	ds_write2_b32 v94, v104, v105 offset0:72 offset1:204
	s_waitcnt lgkmcnt(0)
	s_barrier
	ds_read_b128 v[110:113], v168 offset:62464
	ds_read_b128 v[102:105], v168 offset:62480
	ds_read_b128 v[98:101], v168 offset:62496
	ds_read_b128 v[94:97], v168 offset:62512
	s_waitcnt lgkmcnt(14)
	v_mfma_f32_16x16x32_bf16 v[86:89], v[114:117], v[106:109], v[86:89]
	v_lshlrev_b32_e32 v150, 16, v46
	v_lshlrev_b32_e32 v151, 16, v47
	s_mov_b32 s30, 0x5f901000
	s_waitcnt lgkmcnt(13)
	v_mfma_f32_16x16x32_bf16 v[90:93], v[178:181], v[106:109], v[90:93]
	s_waitcnt lgkmcnt(3)
	v_pk_mul_f32 v[106:107], v[112:113], v[112:113]
	v_pk_mul_f32 v[108:109], v[110:111], v[110:111]
	s_nop 0
	v_pk_mov_b32 v[114:115], v[108:109], v[106:107] op_sel:[1,0]
	v_mov_b32_e32 v109, v107
	v_pk_add_f32 v[106:107], v[114:115], v[108:109]
	s_waitcnt lgkmcnt(2)
	v_pk_mul_f32 v[108:109], v[104:105], v[104:105]
	v_pk_mul_f32 v[114:115], v[102:103], v[102:103]
	v_pk_add_f32 v[106:107], v[106:107], v[106:107] op_sel:[0,1] op_sel_hi:[1,0]
	v_pk_mov_b32 v[116:117], v[114:115], v[108:109] op_sel:[1,0]
	v_mov_b32_e32 v115, v109
	v_pk_add_f32 v[108:109], v[116:117], v[114:115]
	s_waitcnt lgkmcnt(0)
	v_mul_f32_e32 v114, v94, v94
	v_mul_f32_e32 v115, v95, v95
	v_pk_add_f32 v[108:109], v[108:109], v[108:109] op_sel:[0,1] op_sel_hi:[1,0]
	v_mov_b32_e32 v107, v114
	v_mov_b32_e32 v109, v115
	v_pk_add_f32 v[106:107], v[106:107], v[108:109]
	v_mul_f32_e32 v108, v99, v99
	v_mul_f32_e32 v114, v101, v101
	v_mul_f32_e32 v116, v96, v96
	v_mul_f32_e32 v117, v97, v97
	v_pk_fma_f32 v[108:109], v[98:99], v[98:99], v[108:109] op_sel_hi:[1,1,0]
	v_pk_fma_f32 v[114:115], v[100:101], v[100:101], v[114:115] op_sel_hi:[1,1,0]
	v_mov_b32_e32 v109, v116
	v_mov_b32_e32 v115, v117
	v_pk_add_f32 v[108:109], v[108:109], v[114:115]
	v_mfma_f32_16x16x32_bf16 v[86:89], v[170:173], v[144:147], v[86:89]
	v_add_f32_e64 v106, v106, v108
	v_add_f32_e64 v107, v107, v109
	v_and_b32_e32 v108, 64, v235
	v_add_f32_e32 v106, v106, v107
	v_xor_b32_e32 v107, 1, v235
	v_add_u32_e32 v108, 64, v108
	v_cmp_lt_i32_e32 vcc, v107, v108
	v_mfma_f32_16x16x32_bf16 v[90:93], v[186:189], v[144:147], v[90:93]
	v_and_b32_e32 v146, 0xffff0000, v46
	v_cndmask_b32_e32 v107, v235, v107, vcc
	v_lshlrev_b32_e32 v107, 2, v107
	ds_bpermute_b32 v107, v107, v106
	v_and_b32_e32 v147, 0xffff0000, v47
	v_lshl_add_u64 v[144:145], v[134:135], 0, s[6:7]
	s_waitcnt lgkmcnt(0)
	v_add_f32_e32 v106, v106, v107
	v_xor_b32_e32 v107, 2, v235
	v_cmp_lt_i32_e32 vcc, v107, v108
	s_nop 1
	v_cndmask_b32_e32 v107, v235, v107, vcc
	v_lshlrev_b32_e32 v107, 2, v107
	ds_bpermute_b32 v107, v107, v106
	s_waitcnt lgkmcnt(0)
	v_add_f32_e32 v106, v106, v107
	v_xor_b32_e32 v107, 4, v235
	v_cmp_lt_i32_e32 vcc, v107, v108
	s_nop 1
	v_cndmask_b32_e32 v107, v235, v107, vcc
	v_lshlrev_b32_e32 v107, 2, v107
	ds_bpermute_b32 v107, v107, v106
	s_waitcnt lgkmcnt(0)
	v_add_f32_e32 v106, v106, v107
	v_fmamk_f32 v106, v106, 0x3c000000, v1
	v_cmp_gt_f32_e32 vcc, s0, v106
	v_mul_f32_e32 v107, 0x4b800000, v106
	s_nop 0
	v_cndmask_b32_e32 v106, v106, v107, vcc
	v_rsq_f32_e32 v106, v106
	s_nop 0
	v_mul_f32_e32 v107, 0x45800000, v106
	v_cndmask_b32_e32 v142, v106, v107, vcc
	v_mul_f32_e32 v106, 0xbfb8aa3b, v150
	v_exp_f32_e32 v106, v106
	v_mov_b32_e32 v107, v112
	v_mov_b32_e32 v112, v111
	v_add_f32_e32 v106, 1.0, v106
	v_rcp_f32_e32 v152, v106
	v_mul_f32_e32 v106, 0xbfb8aa3b, v146
	v_exp_f32_e32 v106, v106
	s_nop 0
	v_add_f32_e32 v106, 1.0, v106
	v_rcp_f32_e32 v148, v106
	v_mov_b32_e32 v106, v110
	v_pk_mul_f32 v[154:155], v[106:107], v[142:143] op_sel_hi:[1,0]
	v_mov_b32_e32 v106, v246
	v_mov_b32_e32 v107, v247
	v_mov_b32_e32 v108, v248
	v_mov_b32_e32 v109, v249
	v_mov_b32_e32 v114, v242
	v_mov_b32_e32 v115, v243
	v_mov_b32_e32 v116, v244
	v_mov_b32_e32 v117, v245
	v_mul_f32_e32 v110, 0xbfb8aa3b, v151
	v_exp_f32_e32 v110, v110
	v_mov_b32_e32 v171, v116
	v_add_f32_e32 v110, 1.0, v110
	v_rcp_f32_e32 v153, v110
	v_pk_mul_f32 v[110:111], v[112:113], v[142:143] op_sel_hi:[1,0]
	v_mul_f32_e32 v112, 0xbfb8aa3b, v147
	v_exp_f32_e32 v112, v112
	v_mov_b32_e32 v116, v115
	v_pk_mul_f32 v[110:111], v[116:117], v[110:111]
	v_mov_b32_e32 v170, v114
	v_add_f32_e32 v112, 1.0, v112
	v_rcp_f32_e32 v149, v112
	v_and_b32_e32 v114, 0xffff0000, v48
	v_mul_f32_e32 v117, 0xbfb8aa3b, v114
	v_exp_f32_e32 v117, v117
	v_pk_mul_f32 v[112:113], v[148:149], v[146:147]
	v_mov_b32_e32 v148, v102
	v_pk_mul_f32 v[110:111], v[112:113], v[110:111]
	v_lshlrev_b32_e32 v113, 16, v49
	v_mul_f32_e32 v102, 0xbfb8aa3b, v113
	v_exp_f32_e32 v102, v102
	v_and_b32_e32 v115, 0xffff0000, v49
	v_add_f32_e32 v117, 1.0, v117
	v_mov_b32_e32 v149, v104
	v_add_f32_e32 v102, 1.0, v102
	v_mov_b32_e32 v104, v103
	v_lshlrev_b32_e32 v112, 16, v48
	v_rcp_f32_e32 v146, v117
	v_rcp_f32_e32 v117, v102
	v_pk_mul_f32 v[102:103], v[104:105], v[142:143] op_sel_hi:[1,0]
	v_mul_f32_e32 v104, 0xbfb8aa3b, v115
	v_mul_f32_e32 v116, 0xbfb8aa3b, v112
	v_exp_f32_e32 v104, v104
	v_exp_f32_e32 v116, v116
	v_pk_mul_f32 v[150:151], v[152:153], v[150:151]
	v_mov_b32_e32 v153, v108
	v_add_f32_e32 v104, 1.0, v104
	v_add_f32_e32 v116, 1.0, v116
	v_rcp_f32_e32 v147, v104
	v_rcp_f32_e32 v116, v116
	v_mov_b32_e32 v108, v107
	v_pk_mul_f32 v[148:149], v[148:149], v[142:143] op_sel_hi:[1,0]
	v_mov_b32_e32 v152, v106
	v_pk_mul_f32 v[102:103], v[108:109], v[102:103]
	v_pk_mul_f32 v[104:105], v[146:147], v[114:115]
	v_pk_mul_f32 v[154:155], v[170:171], v[154:155]
	v_pk_mul_f32 v[148:149], v[152:153], v[148:149]
	v_pk_mul_f32 v[112:113], v[116:117], v[112:113]
	v_pk_mul_f32 v[102:103], v[104:105], v[102:103]
	v_pk_mul_f32 v[150:151], v[150:151], v[154:155]
	v_pk_mul_f32 v[112:113], v[112:113], v[148:149]
	v_bfe_u32 v105, v102, 16, 1
	v_bfe_u32 v104, v103, 16, 1
	v_add3_u32 v102, v102, v105, s33
	v_bfe_u32 v105, v151, 16, 1
	v_bfe_u32 v109, v113, 16, 1
	v_bfe_u32 v106, v111, 16, 1
	v_add3_u32 v103, v103, v104, s33
	v_bfe_u32 v104, v150, 16, 1
	v_bfe_u32 v108, v112, 16, 1
	v_add3_u32 v109, v113, v109, s33
	v_add3_u32 v105, v151, v105, s33
	v_bfe_u32 v107, v110, 16, 1
	v_add3_u32 v106, v111, v106, s33
	v_add3_u32 v108, v112, v108, s33
	v_add3_u32 v104, v150, v104, s33
	v_lshrrev_b32_e32 v111, 16, v105
	v_lshrrev_b32_e32 v105, 16, v109
	v_add3_u32 v107, v110, v107, s33
	v_lshrrev_b32_e32 v110, 16, v104
	v_lshrrev_b32_e32 v104, 16, v108
	v_and_or_b32 v105, v103, s21, v105
	v_and_or_b32 v103, v106, s21, v111
	v_add_co_u32_e32 v106, vcc, s30, v144
	v_and_or_b32 v104, v102, s21, v104
	v_and_or_b32 v102, v107, s21, v110
	v_addc_co_u32_e32 v107, vcc, 0, v145, vcc
	v_lshlrev_b32_e32 v114, 16, v50
	global_store_dwordx4 v[106:107], v[102:105], off offset:1024
	v_and_b32_e32 v108, 0xffff0000, v50
	v_lshlrev_b32_e32 v115, 16, v51
	v_mul_f32_e32 v102, 0xbfb8aa3b, v114
	v_exp_f32_e32 v102, v102
	v_mov_b32_e32 v103, v100
	v_and_b32_e32 v109, 0xffff0000, v51
	v_mov_b32_e32 v100, v99
	v_add_f32_e32 v102, 1.0, v102
	v_rcp_f32_e32 v116, v102
	v_mul_f32_e32 v102, 0xbfb8aa3b, v108
	v_exp_f32_e32 v102, v102
	s_andn2_b64 vcc, exec, s[8:9]
	v_add_f32_e32 v102, 1.0, v102
	v_rcp_f32_e32 v144, v102
	v_mov_b32_e32 v102, v98
	v_pk_mul_f32 v[146:147], v[102:103], v[142:143] op_sel_hi:[1,0]
	v_mov_b32_e32 v102, v230
	v_mov_b32_e32 v103, v234
	v_mov_b32_e32 v104, v236
	v_mov_b32_e32 v105, v238
	v_mov_b32_e32 v110, v250
	v_mov_b32_e32 v111, v251
	v_mov_b32_e32 v112, v241
	v_mov_b32_e32 v113, v228
	v_mul_f32_e32 v98, 0xbfb8aa3b, v115
	v_exp_f32_e32 v98, v98
	v_mov_b32_e32 v149, v112
	v_add_f32_e32 v98, 1.0, v98
	v_rcp_f32_e32 v117, v98
	v_pk_mul_f32 v[98:99], v[100:101], v[142:143] op_sel_hi:[1,0]
	v_mul_f32_e32 v100, 0xbfb8aa3b, v109
	v_exp_f32_e32 v100, v100
	v_mov_b32_e32 v112, v111
	v_pk_mul_f32 v[98:99], v[112:113], v[98:99]
	v_pk_mul_f32 v[114:115], v[116:117], v[114:115]
	v_add_f32_e32 v100, 1.0, v100
	v_rcp_f32_e32 v145, v100
	v_mov_b32_e32 v116, v94
	v_mov_b32_e32 v117, v96
	v_mov_b32_e32 v96, v95
	v_pk_mul_f32 v[100:101], v[144:145], v[108:109]
	v_and_b32_e32 v108, 0xffff0000, v52
	v_pk_mul_f32 v[98:99], v[100:101], v[98:99]
	v_lshlrev_b32_e32 v101, 16, v53
	v_mul_f32_e32 v111, 0xbfb8aa3b, v108
	v_mul_f32_e32 v94, 0xbfb8aa3b, v101
	v_exp_f32_e32 v111, v111
	v_exp_f32_e32 v94, v94
	v_and_b32_e32 v109, 0xffff0000, v53
	v_lshlrev_b32_e32 v100, 16, v52
	v_add_f32_e32 v111, 1.0, v111
	v_add_f32_e32 v94, 1.0, v94
	v_rcp_f32_e32 v112, v111
	v_rcp_f32_e32 v111, v94
	v_pk_mul_f32 v[94:95], v[96:97], v[142:143] op_sel_hi:[1,0]
	v_mul_f32_e32 v96, 0xbfb8aa3b, v109
	v_mov_b32_e32 v148, v110
	v_mul_f32_e32 v110, 0xbfb8aa3b, v100
	v_exp_f32_e32 v96, v96
	v_exp_f32_e32 v110, v110
	v_mov_b32_e32 v145, v104
	v_mov_b32_e32 v104, v103
	v_add_f32_e32 v96, 1.0, v96
	v_add_f32_e32 v110, 1.0, v110
	v_rcp_f32_e32 v113, v96
	v_rcp_f32_e32 v110, v110
	v_pk_mul_f32 v[116:117], v[116:117], v[142:143] op_sel_hi:[1,0]
	v_mov_b32_e32 v144, v102
	v_pk_mul_f32 v[94:95], v[94:95], v[104:105]
	v_pk_mul_f32 v[96:97], v[112:113], v[108:109]
	v_pk_mul_f32 v[146:147], v[148:149], v[146:147]
	v_pk_mul_f32 v[116:117], v[116:117], v[144:145]
	v_pk_mul_f32 v[100:101], v[110:111], v[100:101]
	v_pk_mul_f32 v[94:95], v[96:97], v[94:95]
	v_pk_mul_f32 v[114:115], v[114:115], v[146:147]
	v_pk_mul_f32 v[100:101], v[100:101], v[116:117]
	v_bfe_u32 v96, v95, 16, 1
	v_bfe_u32 v97, v94, 16, 1
	v_bfe_u32 v102, v99, 16, 1
	v_bfe_u32 v103, v98, 16, 1
	v_add3_u32 v98, v98, v103, s33
	v_add3_u32 v99, v99, v102, s33
	v_add3_u32 v94, v94, v97, s33
	v_add3_u32 v95, v95, v96, s33
	v_bfe_u32 v96, v114, 16, 1
	v_bfe_u32 v97, v115, 16, 1
	v_bfe_u32 v102, v100, 16, 1
	v_bfe_u32 v103, v101, 16, 1
	v_add3_u32 v101, v101, v103, s33
	v_add3_u32 v100, v100, v102, s33
	v_add3_u32 v97, v115, v97, s33
	v_add3_u32 v96, v114, v96, s33
	v_lshrrev_b32_e32 v102, 16, v96
	v_lshrrev_b32_e32 v103, 16, v97
	v_lshrrev_b32_e32 v96, 16, v100
	v_lshrrev_b32_e32 v97, 16, v101
	v_and_or_b32 v97, v95, s21, v97
	v_and_or_b32 v96, v94, s21, v96
	v_and_or_b32 v95, v99, s21, v103
	v_and_or_b32 v94, v98, s21, v102
	global_store_dwordx4 v[106:107], v[94:97], off offset:1040
	s_cbranch_vccnz .LBB0_444
	s_waitcnt vmcnt(2)
	v_mov_b64_e32 v[46:47], v[58:59]
	v_mov_b64_e32 v[50:51], v[54:55]
	v_mov_b64_e32 v[48:49], v[60:61]
	v_mov_b64_e32 v[52:53], v[56:57]
	v_mov_b32_e32 v130, v162
	ds_write_b128 v119, v[2:5]
	ds_write_b128 v156, v[6:9]
	ds_write_b128 v119, v[10:13] offset:17408
	ds_write_b128 v156, v[14:17] offset:17408
	ds_write_b128 v143, v[18:21] offset:34816
	ds_write_b128 v143, v[22:25] offset:44032
	ds_write_b128 v157, v[26:29] offset:44032
	ds_write_b128 v158, v[30:33]
	ds_write_b128 v159, v[34:37]
	ds_write_b128 v160, v[38:41]
	ds_write_b128 v161, v[42:45]
	s_branch .LBB0_444
